# epilogue yield front-loaded: s_sleep 60 after row groups 1-3 only
# speedup vs baseline: 1.0002x; 1.0002x over previous
.LBB0_1163:
	s_ashr_i32 s17, s54, 3
	s_mul_hi_i32 s19, s17, 0x9000
	s_mul_i32 s17, s17, 0x9000
	s_add_u32 s26, s10, s17
	s_addc_u32 s27, s11, s19
	v_lshl_add_u64 v[162:163], s[26:27], 0, v[160:161]
	global_load_dwordx4 v[64:67], v[162:163], off
	v_readlane_b32 s26, v255, 5
	v_readlane_b32 s27, v255, 6
	s_lshl_b32 s17, s54, 8
	v_add_u32_e32 v194, s17, v151
	v_lshl_add_u64 v[166:167], s[26:27], 0, v[160:161]
	v_readlane_b32 s26, v255, 9
	v_readlane_b32 s27, v255, 10
	v_ashrrev_i32_e32 v195, 31, v194
	v_lshl_add_u64 v[212:213], v[194:195], 3, s[12:13]
	v_lshl_add_u64 v[168:169], s[26:27], 0, v[160:161]
	v_lshlrev_b64 v[214:215], 12, v[194:195]
	v_lshl_add_u64 v[214:215], s[0:1], 0, v[214:215]
	v_lshl_add_u64 v[214:215], v[214:215], 0, v[160:161]
	s_waitcnt vmcnt(0)
	v_pk_add_f32 v[178:179], v[66:67], 1.0 op_sel_hi:[1,0]
	v_pk_add_f32 v[180:181], v[64:65], 1.0 op_sel_hi:[1,0]
	global_load_dwordx4 v[84:87], v[166:167], off
	global_load_dwordx4 v[64:67], v[168:169], off
	s_waitcnt vmcnt(0)
	v_pk_mul_f32 v[190:191], v[66:67], s[58:59] op_sel_hi:[1,0]
	v_pk_mul_f32 v[192:193], v[64:65], s[58:59] op_sel_hi:[1,0]
	global_load_dwordx4 v[64:67], v[162:163], off offset:64
	s_waitcnt vmcnt(0)
	v_pk_add_f32 v[174:175], v[66:67], 1.0 op_sel_hi:[1,0]
	v_pk_add_f32 v[176:177], v[64:65], 1.0 op_sel_hi:[1,0]
	global_load_dwordx4 v[72:75], v[166:167], off offset:64
	global_load_dwordx4 v[64:67], v[168:169], off offset:64
	s_waitcnt vmcnt(0)
	v_pk_mul_f32 v[186:187], v[66:67], s[58:59] op_sel_hi:[1,0]
	v_pk_mul_f32 v[188:189], v[64:65], s[58:59] op_sel_hi:[1,0]
	global_load_dwordx4 v[64:67], v[162:163], off offset:512
	s_waitcnt vmcnt(0)
	v_pk_add_f32 v[170:171], v[66:67], 1.0 op_sel_hi:[1,0]
	v_pk_add_f32 v[172:173], v[64:65], 1.0 op_sel_hi:[1,0]
	global_load_dwordx4 v[68:71], v[166:167], off offset:512
	global_load_dwordx4 v[64:67], v[168:169], off offset:512
	s_waitcnt vmcnt(0)
	v_pk_mul_f32 v[182:183], v[66:67], s[58:59] op_sel_hi:[1,0]
	v_pk_mul_f32 v[184:185], v[64:65], s[58:59] op_sel_hi:[1,0]
	global_load_dwordx4 v[64:67], v[162:163], off offset:576
	s_waitcnt vmcnt(0)
	v_pk_add_f32 v[162:163], v[66:67], 1.0 op_sel_hi:[1,0]
	v_pk_add_f32 v[164:165], v[64:65], 1.0 op_sel_hi:[1,0]
	global_load_dwordx4 v[64:67], v[166:167], off offset:576
	global_load_dwordx4 v[232:235], v[168:169], off offset:576
	s_waitcnt vmcnt(0)
	v_pk_mul_f32 v[166:167], v[234:235], s[58:59] op_sel_hi:[1,0]
	global_load_dwordx2 v[212:213], v[212:213], off
	v_pk_mul_f32 v[168:169], v[232:233], s[58:59] op_sel_hi:[1,0]
	global_load_dwordx4 v[232:235], v[214:215], off
	global_load_dwordx4 v[236:239], v[214:215], off offset:64
	global_load_dwordx4 v[240:243], v[214:215], off offset:512
	global_load_dwordx4 v[244:247], v[214:215], off offset:576
	s_waitcnt vmcnt(4)
	v_mul_f32_e32 v216, 0x3fb504f3, v213
	s_waitcnt vmcnt(3)
	v_sub_f32_e32 v219, v233, v212
	v_sub_f32_e32 v218, v232, v212
	v_sub_f32_e32 v233, v235, v212
	v_sub_f32_e32 v232, v234, v212
	v_pk_mul_f32 v[232:233], v[232:233], v[216:217] op_sel_hi:[1,0]
	v_pk_mul_f32 v[218:219], v[218:219], v[216:217] op_sel_hi:[1,0]
	v_pk_fma_f32 v[232:233], v[86:87], v[232:233], v[190:191]
	v_pk_fma_f32 v[218:219], v[84:85], v[218:219], v[192:193]
	v_pk_fma_f32 v[142:143], v[142:143], v[178:179], v[232:233]
	v_pk_fma_f32 v[140:141], v[140:141], v[180:181], v[218:219]
	global_store_dwordx4 v[214:215], v[140:143], off
	s_waitcnt vmcnt(3)
	s_nop 0
	v_sub_f32_e32 v141, v237, v212
	v_sub_f32_e32 v140, v236, v212
	v_sub_f32_e32 v143, v239, v212
	v_sub_f32_e32 v142, v238, v212
	v_pk_mul_f32 v[142:143], v[142:143], v[216:217] op_sel_hi:[1,0]
	v_pk_mul_f32 v[140:141], v[140:141], v[216:217] op_sel_hi:[1,0]
	v_pk_fma_f32 v[142:143], v[74:75], v[142:143], v[186:187]
	v_pk_fma_f32 v[140:141], v[72:73], v[140:141], v[188:189]
	v_pk_fma_f32 v[138:139], v[138:139], v[174:175], v[142:143]
	v_pk_fma_f32 v[136:137], v[136:137], v[176:177], v[140:141]
	global_store_dwordx4 v[214:215], v[136:139], off offset:64
	s_waitcnt vmcnt(3)
	s_nop 0
	v_sub_f32_e32 v137, v241, v212
	v_sub_f32_e32 v136, v240, v212
	v_sub_f32_e32 v139, v243, v212
	v_sub_f32_e32 v138, v242, v212
	v_pk_mul_f32 v[138:139], v[216:217], v[138:139] op_sel_hi:[0,1]
	v_pk_mul_f32 v[136:137], v[216:217], v[136:137] op_sel_hi:[0,1]
	v_pk_fma_f32 v[136:137], v[68:69], v[136:137], v[184:185]
	v_pk_fma_f32 v[138:139], v[70:71], v[138:139], v[182:183]
	v_pk_fma_f32 v[132:133], v[132:133], v[172:173], v[136:137]
	v_pk_fma_f32 v[134:135], v[134:135], v[170:171], v[138:139]
	global_store_dwordx4 v[214:215], v[132:135], off offset:512
	s_waitcnt vmcnt(3)
	s_nop 0
	v_sub_f32_e32 v133, v245, v212
	v_sub_f32_e32 v132, v244, v212
	v_sub_f32_e32 v135, v247, v212
	v_sub_f32_e32 v134, v246, v212
	v_pk_mul_f32 v[134:135], v[216:217], v[134:135] op_sel_hi:[0,1]
	v_pk_mul_f32 v[132:133], v[216:217], v[132:133] op_sel_hi:[0,1]
	v_pk_fma_f32 v[132:133], v[64:65], v[132:133], v[168:169]
	v_pk_fma_f32 v[134:135], v[66:67], v[134:135], v[166:167]
	v_pk_fma_f32 v[128:129], v[128:129], v[164:165], v[132:133]
	v_pk_fma_f32 v[130:131], v[130:131], v[162:163], v[134:135]
	global_store_dwordx4 v[214:215], v[128:131], off offset:576
	s_and_b64 vcc, exec, s[6:7]
	s_cbranch_vccnz .Lmy_epi_w0
	s_sleep 60
.Lmy_epi_w0:
	s_nop 1
	v_add_u32_e32 v128, s17, v226
	v_ashrrev_i32_e32 v129, 31, v128
	v_lshl_add_u64 v[130:131], v[128:129], 3, s[12:13]
	global_load_dwordx2 v[212:213], v[130:131], off
	v_lshlrev_b64 v[128:129], 12, v[128:129]
	v_lshl_add_u64 v[128:129], s[0:1], 0, v[128:129]
	v_lshl_add_u64 v[214:215], v[128:129], 0, v[160:161]
	global_load_dwordx4 v[128:131], v[214:215], off
	global_load_dwordx4 v[132:135], v[214:215], off offset:64
	global_load_dwordx4 v[136:139], v[214:215], off offset:512
	global_load_dwordx4 v[140:143], v[214:215], off offset:576
	s_waitcnt vmcnt(4)
	v_mul_f32_e32 v216, 0x3fb504f3, v213
	s_waitcnt vmcnt(3)
	v_sub_f32_e32 v129, v129, v212
	v_sub_f32_e32 v128, v128, v212
	v_sub_f32_e32 v131, v131, v212
	v_sub_f32_e32 v130, v130, v212
	v_pk_mul_f32 v[130:131], v[130:131], v[216:217] op_sel_hi:[1,0]
	v_pk_mul_f32 v[128:129], v[128:129], v[216:217] op_sel_hi:[1,0]
	v_pk_fma_f32 v[130:131], v[86:87], v[130:131], v[190:191]
	v_pk_fma_f32 v[128:129], v[84:85], v[128:129], v[192:193]
	v_pk_fma_f32 v[126:127], v[126:127], v[178:179], v[130:131]
	v_pk_fma_f32 v[124:125], v[124:125], v[180:181], v[128:129]
	global_store_dwordx4 v[214:215], v[124:127], off
	s_waitcnt vmcnt(3)
	s_nop 0
	v_sub_f32_e32 v125, v133, v212
	v_sub_f32_e32 v124, v132, v212
	v_sub_f32_e32 v127, v135, v212
	v_sub_f32_e32 v126, v134, v212
	v_pk_mul_f32 v[126:127], v[126:127], v[216:217] op_sel_hi:[1,0]
	v_pk_mul_f32 v[124:125], v[124:125], v[216:217] op_sel_hi:[1,0]
	v_pk_fma_f32 v[126:127], v[74:75], v[126:127], v[186:187]
	v_pk_fma_f32 v[124:125], v[72:73], v[124:125], v[188:189]
	v_pk_fma_f32 v[122:123], v[122:123], v[174:175], v[126:127]
	v_pk_fma_f32 v[120:121], v[120:121], v[176:177], v[124:125]
	global_store_dwordx4 v[214:215], v[120:123], off offset:64
	s_waitcnt vmcnt(3)
	s_nop 0
	v_sub_f32_e32 v121, v137, v212
	v_sub_f32_e32 v120, v136, v212
	v_sub_f32_e32 v123, v139, v212
	v_sub_f32_e32 v122, v138, v212
	v_pk_mul_f32 v[122:123], v[216:217], v[122:123] op_sel_hi:[0,1]
	v_pk_mul_f32 v[120:121], v[216:217], v[120:121] op_sel_hi:[0,1]
	v_pk_fma_f32 v[120:121], v[68:69], v[120:121], v[184:185]
	v_pk_fma_f32 v[122:123], v[70:71], v[122:123], v[182:183]
	v_pk_fma_f32 v[116:117], v[116:117], v[172:173], v[120:121]
	v_pk_fma_f32 v[118:119], v[118:119], v[170:171], v[122:123]
	global_store_dwordx4 v[214:215], v[116:119], off offset:512
	s_waitcnt vmcnt(3)
	s_nop 0
	v_sub_f32_e32 v117, v141, v212
	v_sub_f32_e32 v116, v140, v212
	v_sub_f32_e32 v119, v143, v212
	v_sub_f32_e32 v118, v142, v212
	v_pk_mul_f32 v[118:119], v[216:217], v[118:119] op_sel_hi:[0,1]
	v_pk_mul_f32 v[116:117], v[216:217], v[116:117] op_sel_hi:[0,1]
	v_pk_fma_f32 v[116:117], v[64:65], v[116:117], v[168:169]
	v_pk_fma_f32 v[118:119], v[66:67], v[118:119], v[166:167]
	v_pk_fma_f32 v[112:113], v[112:113], v[164:165], v[116:117]
	v_pk_fma_f32 v[114:115], v[114:115], v[162:163], v[118:119]
	global_store_dwordx4 v[214:215], v[112:115], off offset:576
	s_and_b64 vcc, exec, s[6:7]
	s_cbranch_vccnz .Lmy_epi_w1
	s_sleep 60
.Lmy_epi_w1:
	s_nop 1
	v_add_u32_e32 v112, s17, v227
	v_ashrrev_i32_e32 v113, 31, v112
	v_lshl_add_u64 v[114:115], v[112:113], 3, s[12:13]
	global_load_dwordx2 v[128:129], v[114:115], off
	v_lshlrev_b64 v[112:113], 12, v[112:113]
	v_lshl_add_u64 v[112:113], s[0:1], 0, v[112:113]
	v_lshl_add_u64 v[130:131], v[112:113], 0, v[160:161]
	global_load_dwordx4 v[112:115], v[130:131], off
	global_load_dwordx4 v[116:119], v[130:131], off offset:64
	global_load_dwordx4 v[120:123], v[130:131], off offset:512
	global_load_dwordx4 v[124:127], v[130:131], off offset:576
	s_waitcnt vmcnt(4)
	v_mul_f32_e32 v132, 0x3fb504f3, v129
	s_waitcnt vmcnt(3)
	v_sub_f32_e32 v113, v113, v128
	v_sub_f32_e32 v112, v112, v128
	v_sub_f32_e32 v115, v115, v128
	v_sub_f32_e32 v114, v114, v128
	v_pk_mul_f32 v[114:115], v[114:115], v[132:133] op_sel_hi:[1,0]
	v_pk_mul_f32 v[112:113], v[112:113], v[132:133] op_sel_hi:[1,0]
	v_pk_fma_f32 v[114:115], v[86:87], v[114:115], v[190:191]
	v_pk_fma_f32 v[112:113], v[84:85], v[112:113], v[192:193]
	v_pk_fma_f32 v[110:111], v[110:111], v[178:179], v[114:115]
	v_pk_fma_f32 v[108:109], v[108:109], v[180:181], v[112:113]
	global_store_dwordx4 v[130:131], v[108:111], off
	s_waitcnt vmcnt(3)
	s_nop 0
	v_sub_f32_e32 v109, v117, v128
	v_sub_f32_e32 v108, v116, v128
	v_sub_f32_e32 v111, v119, v128
	v_sub_f32_e32 v110, v118, v128
	v_pk_mul_f32 v[110:111], v[110:111], v[132:133] op_sel_hi:[1,0]
	v_pk_mul_f32 v[108:109], v[108:109], v[132:133] op_sel_hi:[1,0]
	v_pk_fma_f32 v[110:111], v[74:75], v[110:111], v[186:187]
	v_pk_fma_f32 v[108:109], v[72:73], v[108:109], v[188:189]
	v_pk_fma_f32 v[106:107], v[106:107], v[174:175], v[110:111]
	v_pk_fma_f32 v[104:105], v[104:105], v[176:177], v[108:109]
	global_store_dwordx4 v[130:131], v[104:107], off offset:64
	s_waitcnt vmcnt(3)
	s_nop 0
	v_sub_f32_e32 v105, v121, v128
	v_sub_f32_e32 v104, v120, v128
	v_sub_f32_e32 v107, v123, v128
	v_sub_f32_e32 v106, v122, v128
	v_pk_mul_f32 v[106:107], v[132:133], v[106:107] op_sel_hi:[0,1]
	v_pk_mul_f32 v[104:105], v[132:133], v[104:105] op_sel_hi:[0,1]
	v_pk_fma_f32 v[104:105], v[68:69], v[104:105], v[184:185]
	v_pk_fma_f32 v[106:107], v[70:71], v[106:107], v[182:183]
	v_pk_fma_f32 v[100:101], v[100:101], v[172:173], v[104:105]
	v_pk_fma_f32 v[102:103], v[102:103], v[170:171], v[106:107]
	global_store_dwordx4 v[130:131], v[100:103], off offset:512
	s_waitcnt vmcnt(3)
	s_nop 0
	v_sub_f32_e32 v101, v125, v128
	v_sub_f32_e32 v100, v124, v128
	v_sub_f32_e32 v103, v127, v128
	v_sub_f32_e32 v102, v126, v128
	v_pk_mul_f32 v[102:103], v[132:133], v[102:103] op_sel_hi:[0,1]
	v_pk_mul_f32 v[100:101], v[132:133], v[100:101] op_sel_hi:[0,1]
	v_pk_fma_f32 v[100:101], v[64:65], v[100:101], v[168:169]
	v_pk_fma_f32 v[102:103], v[66:67], v[102:103], v[166:167]
	v_pk_fma_f32 v[96:97], v[96:97], v[164:165], v[100:101]
	v_pk_fma_f32 v[98:99], v[98:99], v[162:163], v[102:103]
	global_store_dwordx4 v[130:131], v[96:99], off offset:576
	s_and_b64 vcc, exec, s[6:7]
	s_cbranch_vccnz .Lmy_epi_w2
	s_sleep 60
.Lmy_epi_w2:
	s_nop 1
	v_add_u32_e32 v96, s17, v228
	v_ashrrev_i32_e32 v97, 31, v96
	v_lshl_add_u64 v[98:99], v[96:97], 3, s[12:13]
	global_load_dwordx2 v[112:113], v[98:99], off
	v_lshlrev_b64 v[96:97], 12, v[96:97]
	v_lshl_add_u64 v[96:97], s[0:1], 0, v[96:97]
	v_lshl_add_u64 v[114:115], v[96:97], 0, v[160:161]
	global_load_dwordx4 v[96:99], v[114:115], off
	global_load_dwordx4 v[100:103], v[114:115], off offset:64
	global_load_dwordx4 v[104:107], v[114:115], off offset:512
	global_load_dwordx4 v[108:111], v[114:115], off offset:576
	s_waitcnt vmcnt(4)
	v_mul_f32_e32 v116, 0x3fb504f3, v113
	s_waitcnt vmcnt(3)
	v_sub_f32_e32 v97, v97, v112
	v_sub_f32_e32 v96, v96, v112
	v_sub_f32_e32 v99, v99, v112
	v_sub_f32_e32 v98, v98, v112
	v_pk_mul_f32 v[98:99], v[98:99], v[116:117] op_sel_hi:[1,0]
	v_pk_mul_f32 v[96:97], v[96:97], v[116:117] op_sel_hi:[1,0]
	v_pk_fma_f32 v[98:99], v[86:87], v[98:99], v[190:191]
	v_pk_fma_f32 v[96:97], v[84:85], v[96:97], v[192:193]
	v_pk_fma_f32 v[94:95], v[94:95], v[178:179], v[98:99]
	v_pk_fma_f32 v[92:93], v[92:93], v[180:181], v[96:97]
	global_store_dwordx4 v[114:115], v[92:95], off
	s_waitcnt vmcnt(3)
	s_nop 0
	v_sub_f32_e32 v93, v101, v112
	v_sub_f32_e32 v92, v100, v112
	v_sub_f32_e32 v95, v103, v112
	v_sub_f32_e32 v94, v102, v112
	v_pk_mul_f32 v[94:95], v[94:95], v[116:117] op_sel_hi:[1,0]
	v_pk_mul_f32 v[92:93], v[92:93], v[116:117] op_sel_hi:[1,0]
	v_pk_fma_f32 v[94:95], v[74:75], v[94:95], v[186:187]
	v_pk_fma_f32 v[92:93], v[72:73], v[92:93], v[188:189]
	v_pk_fma_f32 v[90:91], v[90:91], v[174:175], v[94:95]
	v_pk_fma_f32 v[88:89], v[88:89], v[176:177], v[92:93]
	global_store_dwordx4 v[114:115], v[88:91], off offset:64
	s_waitcnt vmcnt(3)
	s_nop 0
	v_sub_f32_e32 v89, v105, v112
	v_sub_f32_e32 v88, v104, v112
	v_sub_f32_e32 v91, v107, v112
	v_sub_f32_e32 v90, v106, v112
	v_pk_mul_f32 v[90:91], v[116:117], v[90:91] op_sel_hi:[0,1]
	v_pk_mul_f32 v[88:89], v[116:117], v[88:89] op_sel_hi:[0,1]
	v_pk_fma_f32 v[88:89], v[68:69], v[88:89], v[184:185]
	v_pk_fma_f32 v[90:91], v[70:71], v[90:91], v[182:183]
	v_pk_fma_f32 v[80:81], v[80:81], v[172:173], v[88:89]
	v_pk_fma_f32 v[82:83], v[82:83], v[170:171], v[90:91]
	global_store_dwordx4 v[114:115], v[80:83], off offset:512
	s_waitcnt vmcnt(3)
	s_nop 0
	v_sub_f32_e32 v81, v109, v112
	v_sub_f32_e32 v80, v108, v112
	v_sub_f32_e32 v83, v111, v112
	v_sub_f32_e32 v82, v110, v112
	v_pk_mul_f32 v[82:83], v[116:117], v[82:83] op_sel_hi:[0,1]
	v_pk_mul_f32 v[80:81], v[116:117], v[80:81] op_sel_hi:[0,1]
	v_pk_fma_f32 v[80:81], v[64:65], v[80:81], v[168:169]
	v_pk_fma_f32 v[82:83], v[66:67], v[82:83], v[166:167]
	v_pk_fma_f32 v[76:77], v[76:77], v[164:165], v[80:81]
	v_pk_fma_f32 v[78:79], v[78:79], v[162:163], v[82:83]
	global_store_dwordx4 v[114:115], v[76:79], off offset:576
	s_nop 1
	v_add_u32_e32 v76, 0x80, v194
	v_ashrrev_i32_e32 v77, 31, v76
	v_lshl_add_u64 v[78:79], v[76:77], 3, s[12:13]
	global_load_dwordx2 v[96:97], v[78:79], off
	v_lshlrev_b64 v[76:77], 12, v[76:77]
	v_lshl_add_u64 v[76:77], s[0:1], 0, v[76:77]
	v_lshl_add_u64 v[98:99], v[76:77], 0, v[160:161]
	global_load_dwordx4 v[76:79], v[98:99], off
	global_load_dwordx4 v[80:83], v[98:99], off offset:64
	global_load_dwordx4 v[88:91], v[98:99], off offset:512
	global_load_dwordx4 v[92:95], v[98:99], off offset:576
	s_waitcnt vmcnt(4)
	v_mul_f32_e32 v100, 0x3fb504f3, v97
	s_waitcnt vmcnt(3)
	v_sub_f32_e32 v77, v77, v96
	v_sub_f32_e32 v76, v76, v96
	v_sub_f32_e32 v79, v79, v96
	v_sub_f32_e32 v78, v78, v96
	v_pk_mul_f32 v[78:79], v[78:79], v[100:101] op_sel_hi:[1,0]
	v_pk_mul_f32 v[76:77], v[76:77], v[100:101] op_sel_hi:[1,0]
	v_pk_fma_f32 v[78:79], v[86:87], v[78:79], v[190:191]
	v_pk_fma_f32 v[76:77], v[84:85], v[76:77], v[192:193]
	v_pk_fma_f32 v[62:63], v[62:63], v[178:179], v[78:79]
	v_pk_fma_f32 v[60:61], v[60:61], v[180:181], v[76:77]
	global_store_dwordx4 v[98:99], v[60:63], off
	s_waitcnt vmcnt(3)
	s_nop 0
	v_sub_f32_e32 v61, v81, v96
	v_sub_f32_e32 v60, v80, v96
	v_sub_f32_e32 v63, v83, v96
	v_sub_f32_e32 v62, v82, v96
	v_pk_mul_f32 v[62:63], v[62:63], v[100:101] op_sel_hi:[1,0]
	v_pk_mul_f32 v[60:61], v[60:61], v[100:101] op_sel_hi:[1,0]
	v_pk_fma_f32 v[62:63], v[74:75], v[62:63], v[186:187]
	v_pk_fma_f32 v[60:61], v[72:73], v[60:61], v[188:189]
	v_pk_fma_f32 v[58:59], v[58:59], v[174:175], v[62:63]
	v_pk_fma_f32 v[56:57], v[56:57], v[176:177], v[60:61]
	global_store_dwordx4 v[98:99], v[56:59], off offset:64
	s_waitcnt vmcnt(3)
	s_nop 0
	v_sub_f32_e32 v57, v89, v96
	v_sub_f32_e32 v56, v88, v96
	v_sub_f32_e32 v59, v91, v96
	v_sub_f32_e32 v58, v90, v96
	v_pk_mul_f32 v[58:59], v[100:101], v[58:59] op_sel_hi:[0,1]
	v_pk_mul_f32 v[56:57], v[100:101], v[56:57] op_sel_hi:[0,1]
	v_pk_fma_f32 v[56:57], v[68:69], v[56:57], v[184:185]
	v_pk_fma_f32 v[58:59], v[70:71], v[58:59], v[182:183]
	v_pk_fma_f32 v[52:53], v[52:53], v[172:173], v[56:57]
	v_pk_fma_f32 v[54:55], v[54:55], v[170:171], v[58:59]
	global_store_dwordx4 v[98:99], v[52:55], off offset:512
	s_waitcnt vmcnt(3)
	s_nop 0
	v_sub_f32_e32 v53, v93, v96
	v_sub_f32_e32 v52, v92, v96
	v_sub_f32_e32 v55, v95, v96
	v_sub_f32_e32 v54, v94, v96
	v_pk_mul_f32 v[54:55], v[100:101], v[54:55] op_sel_hi:[0,1]
	v_pk_mul_f32 v[52:53], v[100:101], v[52:53] op_sel_hi:[0,1]
	v_pk_fma_f32 v[52:53], v[64:65], v[52:53], v[168:169]
	v_pk_fma_f32 v[54:55], v[66:67], v[54:55], v[166:167]
	v_pk_fma_f32 v[48:49], v[48:49], v[164:165], v[52:53]
	v_pk_fma_f32 v[50:51], v[50:51], v[162:163], v[54:55]
	global_store_dwordx4 v[98:99], v[48:51], off offset:576
	s_nop 1
	v_add_u32_e32 v48, 0x90, v194
	v_ashrrev_i32_e32 v49, 31, v48
	v_lshl_add_u64 v[50:51], v[48:49], 3, s[12:13]
	global_load_dwordx2 v[76:77], v[50:51], off
	v_lshlrev_b64 v[48:49], 12, v[48:49]
	v_lshl_add_u64 v[48:49], s[0:1], 0, v[48:49]
	v_lshl_add_u64 v[78:79], v[48:49], 0, v[160:161]
	global_load_dwordx4 v[48:51], v[78:79], off
	global_load_dwordx4 v[52:55], v[78:79], off offset:64
	global_load_dwordx4 v[56:59], v[78:79], off offset:512
	global_load_dwordx4 v[60:63], v[78:79], off offset:576
	s_waitcnt vmcnt(4)
	v_mul_f32_e32 v80, 0x3fb504f3, v77
	s_waitcnt vmcnt(3)
	v_sub_f32_e32 v49, v49, v76
	v_sub_f32_e32 v48, v48, v76
	v_sub_f32_e32 v51, v51, v76
	v_sub_f32_e32 v50, v50, v76
	v_pk_mul_f32 v[50:51], v[50:51], v[80:81] op_sel_hi:[1,0]
	v_pk_mul_f32 v[48:49], v[48:49], v[80:81] op_sel_hi:[1,0]
	v_pk_fma_f32 v[50:51], v[86:87], v[50:51], v[190:191]
	v_pk_fma_f32 v[48:49], v[84:85], v[48:49], v[192:193]
	v_pk_fma_f32 v[46:47], v[46:47], v[178:179], v[50:51]
	v_pk_fma_f32 v[44:45], v[44:45], v[180:181], v[48:49]
	global_store_dwordx4 v[78:79], v[44:47], off
	s_waitcnt vmcnt(3)
	s_nop 0
	v_sub_f32_e32 v45, v53, v76
	v_sub_f32_e32 v44, v52, v76
	v_sub_f32_e32 v47, v55, v76
	v_sub_f32_e32 v46, v54, v76
	v_pk_mul_f32 v[46:47], v[46:47], v[80:81] op_sel_hi:[1,0]
	v_pk_mul_f32 v[44:45], v[44:45], v[80:81] op_sel_hi:[1,0]
	v_pk_fma_f32 v[46:47], v[74:75], v[46:47], v[186:187]
	v_pk_fma_f32 v[44:45], v[72:73], v[44:45], v[188:189]
	v_pk_fma_f32 v[42:43], v[42:43], v[174:175], v[46:47]
	v_pk_fma_f32 v[40:41], v[40:41], v[176:177], v[44:45]
	global_store_dwordx4 v[78:79], v[40:43], off offset:64
	s_waitcnt vmcnt(3)
	s_nop 0
	v_sub_f32_e32 v41, v57, v76
	v_sub_f32_e32 v40, v56, v76
	v_sub_f32_e32 v43, v59, v76
	v_sub_f32_e32 v42, v58, v76
	v_pk_mul_f32 v[42:43], v[80:81], v[42:43] op_sel_hi:[0,1]
	v_pk_mul_f32 v[40:41], v[80:81], v[40:41] op_sel_hi:[0,1]
	v_pk_fma_f32 v[40:41], v[68:69], v[40:41], v[184:185]
	v_pk_fma_f32 v[42:43], v[70:71], v[42:43], v[182:183]
	v_pk_fma_f32 v[36:37], v[36:37], v[172:173], v[40:41]
	v_pk_fma_f32 v[38:39], v[38:39], v[170:171], v[42:43]
	global_store_dwordx4 v[78:79], v[36:39], off offset:512
	s_waitcnt vmcnt(3)
	s_nop 0
	v_sub_f32_e32 v37, v61, v76
	v_sub_f32_e32 v36, v60, v76
	v_sub_f32_e32 v39, v63, v76
	v_sub_f32_e32 v38, v62, v76
	v_pk_mul_f32 v[38:39], v[80:81], v[38:39] op_sel_hi:[0,1]
	v_pk_mul_f32 v[36:37], v[80:81], v[36:37] op_sel_hi:[0,1]
	v_pk_fma_f32 v[36:37], v[64:65], v[36:37], v[168:169]
	v_pk_fma_f32 v[38:39], v[66:67], v[38:39], v[166:167]
	v_pk_fma_f32 v[32:33], v[32:33], v[164:165], v[36:37]
	v_pk_fma_f32 v[34:35], v[34:35], v[162:163], v[38:39]
	global_store_dwordx4 v[78:79], v[32:35], off offset:576
	s_nop 1
	v_add_u32_e32 v32, 0xa0, v194
	v_ashrrev_i32_e32 v33, 31, v32
	v_lshl_add_u64 v[34:35], v[32:33], 3, s[12:13]
	global_load_dwordx2 v[48:49], v[34:35], off
	v_lshlrev_b64 v[32:33], 12, v[32:33]
	v_lshl_add_u64 v[32:33], s[0:1], 0, v[32:33]
	v_lshl_add_u64 v[50:51], v[32:33], 0, v[160:161]
	global_load_dwordx4 v[32:35], v[50:51], off
	global_load_dwordx4 v[36:39], v[50:51], off offset:64
	global_load_dwordx4 v[40:43], v[50:51], off offset:512
	global_load_dwordx4 v[44:47], v[50:51], off offset:576
	s_waitcnt vmcnt(4)
	v_mul_f32_e32 v52, 0x3fb504f3, v49
	s_waitcnt vmcnt(3)
	v_sub_f32_e32 v33, v33, v48
	v_sub_f32_e32 v32, v32, v48
	v_sub_f32_e32 v35, v35, v48
	v_sub_f32_e32 v34, v34, v48
	v_pk_mul_f32 v[34:35], v[34:35], v[52:53] op_sel_hi:[1,0]
	v_pk_mul_f32 v[32:33], v[32:33], v[52:53] op_sel_hi:[1,0]
	v_pk_fma_f32 v[34:35], v[86:87], v[34:35], v[190:191]
	v_pk_fma_f32 v[32:33], v[84:85], v[32:33], v[192:193]
	v_pk_fma_f32 v[30:31], v[30:31], v[178:179], v[34:35]
	v_pk_fma_f32 v[28:29], v[28:29], v[180:181], v[32:33]
	global_store_dwordx4 v[50:51], v[28:31], off
	s_waitcnt vmcnt(3)
	s_nop 0
	v_sub_f32_e32 v29, v37, v48
	v_sub_f32_e32 v28, v36, v48
	v_sub_f32_e32 v31, v39, v48
	v_sub_f32_e32 v30, v38, v48
	v_pk_mul_f32 v[30:31], v[30:31], v[52:53] op_sel_hi:[1,0]
	v_pk_mul_f32 v[28:29], v[28:29], v[52:53] op_sel_hi:[1,0]
	v_pk_fma_f32 v[30:31], v[74:75], v[30:31], v[186:187]
	v_pk_fma_f32 v[28:29], v[72:73], v[28:29], v[188:189]
	v_pk_fma_f32 v[26:27], v[26:27], v[174:175], v[30:31]
	v_pk_fma_f32 v[24:25], v[24:25], v[176:177], v[28:29]
	global_store_dwordx4 v[50:51], v[24:27], off offset:64
	s_waitcnt vmcnt(3)
	s_nop 0
	v_sub_f32_e32 v25, v41, v48
	v_sub_f32_e32 v24, v40, v48
	v_sub_f32_e32 v27, v43, v48
	v_sub_f32_e32 v26, v42, v48
	v_pk_mul_f32 v[26:27], v[52:53], v[26:27] op_sel_hi:[0,1]
	v_pk_mul_f32 v[24:25], v[52:53], v[24:25] op_sel_hi:[0,1]
	v_pk_fma_f32 v[24:25], v[68:69], v[24:25], v[184:185]
	v_pk_fma_f32 v[26:27], v[70:71], v[26:27], v[182:183]
	v_pk_fma_f32 v[20:21], v[20:21], v[172:173], v[24:25]
	v_pk_fma_f32 v[22:23], v[22:23], v[170:171], v[26:27]
	global_store_dwordx4 v[50:51], v[20:23], off offset:512
	s_waitcnt vmcnt(3)
	s_nop 0
	v_sub_f32_e32 v21, v45, v48
	v_sub_f32_e32 v20, v44, v48
	v_sub_f32_e32 v23, v47, v48
	v_sub_f32_e32 v22, v46, v48
	v_pk_mul_f32 v[22:23], v[52:53], v[22:23] op_sel_hi:[0,1]
	v_pk_mul_f32 v[20:21], v[52:53], v[20:21] op_sel_hi:[0,1]
	v_pk_fma_f32 v[20:21], v[64:65], v[20:21], v[168:169]
	v_pk_fma_f32 v[22:23], v[66:67], v[22:23], v[166:167]
	v_pk_fma_f32 v[16:17], v[16:17], v[164:165], v[20:21]
	v_pk_fma_f32 v[18:19], v[18:19], v[162:163], v[22:23]
	global_store_dwordx4 v[50:51], v[16:19], off offset:576
	s_nop 1
	v_add_u32_e32 v16, 0xb0, v194
	v_ashrrev_i32_e32 v17, 31, v16
	v_lshl_add_u64 v[18:19], v[16:17], 3, s[12:13]
	global_load_dwordx2 v[18:19], v[18:19], off
	v_lshlrev_b64 v[16:17], 12, v[16:17]
	v_lshl_add_u64 v[16:17], s[0:1], 0, v[16:17]
	v_lshl_add_u64 v[16:17], v[16:17], 0, v[160:161]
	global_load_dwordx4 v[20:23], v[16:17], off
	global_load_dwordx4 v[24:27], v[16:17], off offset:64
	global_load_dwordx4 v[28:31], v[16:17], off offset:512
	global_load_dwordx4 v[32:35], v[16:17], off offset:576
	s_waitcnt vmcnt(4)
	v_mul_f32_e32 v36, 0x3fb504f3, v19
	s_waitcnt vmcnt(3)
	v_sub_f32_e32 v21, v21, v18
	v_sub_f32_e32 v20, v20, v18
	v_sub_f32_e32 v23, v23, v18
	v_sub_f32_e32 v22, v22, v18
	v_pk_mul_f32 v[22:23], v[22:23], v[36:37] op_sel_hi:[1,0]
	v_pk_mul_f32 v[20:21], v[20:21], v[36:37] op_sel_hi:[1,0]
	v_pk_fma_f32 v[22:23], v[86:87], v[22:23], v[190:191]
	v_pk_fma_f32 v[20:21], v[84:85], v[20:21], v[192:193]
	v_pk_fma_f32 v[14:15], v[14:15], v[178:179], v[22:23]
	v_pk_fma_f32 v[12:13], v[12:13], v[180:181], v[20:21]
	global_store_dwordx4 v[16:17], v[12:15], off
	s_waitcnt vmcnt(3)
	s_nop 0
	v_sub_f32_e32 v13, v25, v18
	v_sub_f32_e32 v12, v24, v18
	v_sub_f32_e32 v15, v27, v18
	v_sub_f32_e32 v14, v26, v18
	v_pk_mul_f32 v[14:15], v[14:15], v[36:37] op_sel_hi:[1,0]
	v_pk_mul_f32 v[12:13], v[12:13], v[36:37] op_sel_hi:[1,0]
	v_pk_fma_f32 v[14:15], v[74:75], v[14:15], v[186:187]
	v_pk_fma_f32 v[12:13], v[72:73], v[12:13], v[188:189]
	v_pk_fma_f32 v[10:11], v[10:11], v[174:175], v[14:15]
	v_pk_fma_f32 v[8:9], v[8:9], v[176:177], v[12:13]
	global_store_dwordx4 v[16:17], v[8:11], off offset:64
	s_waitcnt vmcnt(3)
	s_nop 0
	v_sub_f32_e32 v9, v29, v18
	v_sub_f32_e32 v8, v28, v18
	v_sub_f32_e32 v11, v31, v18
	v_sub_f32_e32 v10, v30, v18
	v_pk_mul_f32 v[10:11], v[36:37], v[10:11] op_sel_hi:[0,1]
	v_pk_mul_f32 v[8:9], v[36:37], v[8:9] op_sel_hi:[0,1]
	v_pk_fma_f32 v[8:9], v[68:69], v[8:9], v[184:185]
	v_pk_fma_f32 v[10:11], v[70:71], v[10:11], v[182:183]
	v_pk_fma_f32 v[4:5], v[4:5], v[172:173], v[8:9]
	v_pk_fma_f32 v[6:7], v[6:7], v[170:171], v[10:11]
	global_store_dwordx4 v[16:17], v[4:7], off offset:512
	s_waitcnt vmcnt(3)
	s_nop 0
	v_sub_f32_e32 v5, v33, v18
	v_sub_f32_e32 v4, v32, v18
	v_sub_f32_e32 v7, v35, v18
	v_sub_f32_e32 v6, v34, v18
	v_pk_mul_f32 v[6:7], v[36:37], v[6:7] op_sel_hi:[0,1]
	v_pk_mul_f32 v[4:5], v[36:37], v[4:5] op_sel_hi:[0,1]
	v_pk_fma_f32 v[4:5], v[64:65], v[4:5], v[168:169]
	v_pk_fma_f32 v[6:7], v[66:67], v[6:7], v[166:167]
	v_pk_fma_f32 v[0:1], v[0:1], v[164:165], v[4:5]
	v_pk_fma_f32 v[2:3], v[2:3], v[162:163], v[6:7]
	global_store_dwordx4 v[16:17], v[0:3], off offset:576
	s_and_b64 vcc, exec, s[6:7]
	s_mov_b64 s[6:7], -1
	s_cbranch_vccnz .LBB0_1150

.LBB0_1378:
	s_ashr_i32 s25, s76, 3
	s_mul_hi_i32 s35, s25, 0x9000
	s_mul_i32 s25, s25, 0x9000
	s_add_u32 s34, s12, s25
	s_addc_u32 s35, s13, s35
	s_lshl_b32 s25, s76, 8
	v_add_u32_e32 v194, s25, v151
	v_lshl_add_u64 v[128:129], s[20:21], 0, v[160:161]
	v_ashrrev_i32_e32 v195, 31, v194
	global_load_dwordx4 v[162:165], v[128:129], off
	v_lshl_add_u64 v[130:131], s[34:35], 0, v[160:161]
	global_load_dwordx4 v[170:173], v[128:129], off offset:64
	global_load_dwordx4 v[174:177], v[128:129], off offset:512
	global_load_dwordx4 v[178:181], v[130:131], off
	global_load_dwordx4 v[182:185], v[130:131], off offset:64
	global_load_dwordx4 v[232:235], v[128:129], off offset:576
	global_load_dwordx4 v[236:239], v[130:131], off offset:512
	global_load_dwordx4 v[240:243], v[130:131], off offset:576
	v_lshl_add_u64 v[128:129], v[194:195], 3, s[14:15]
	v_lshlrev_b64 v[166:167], 12, v[194:195]
	global_load_dwordx2 v[206:207], v[128:129], off
	v_lshl_add_u64 v[128:129], s[16:17], 0, v[166:167]
	v_lshl_add_u64 v[128:129], v[128:129], 0, v[160:161]
	global_load_dwordx4 v[244:247], v[128:129], off
	global_load_dwordx4 v[248:251], v[128:129], off offset:64
	global_load_dwordx4 v[216:219], v[128:129], off offset:512
	global_load_dwordx4 v[212:215], v[128:129], off offset:576
	v_lshl_add_u64 v[128:129], s[18:19], 0, v[160:161]
	global_load_dwordx4 v[140:143], v[128:129], off
	global_load_dwordx4 v[136:139], v[128:129], off offset:64
	global_load_dwordx4 v[132:135], v[128:129], off offset:512
	s_nop 0
	global_load_dwordx4 v[128:131], v[128:129], off offset:576
	v_lshl_add_u64 v[166:167], s[8:9], 0, v[166:167]
	v_lshl_add_u64 v[198:199], v[166:167], 0, v[160:161]
	s_waitcnt vmcnt(0)
	v_pk_mul_f32 v[168:169], v[172:173], s[58:59] op_sel_hi:[1,0]
	v_pk_mul_f32 v[188:189], v[170:171], s[58:59] op_sel_hi:[1,0]
	v_pk_mul_f32 v[170:171], v[176:177], s[58:59] op_sel_hi:[1,0]
	v_pk_fma_f32 v[176:177], v[178:179], 0.5, 0.5 op_sel_hi:[1,0,0]
	v_pk_mul_f32 v[172:173], v[234:235], s[58:59] op_sel_hi:[1,0]
	v_pk_mul_f32 v[192:193], v[232:233], s[58:59] op_sel_hi:[1,0]
	v_pk_fma_f32 v[178:179], v[184:185], 0.5, 0.5 op_sel_hi:[1,0,0]
	v_pk_fma_f32 v[184:185], v[236:237], 0.5, 0.5 op_sel_hi:[1,0,0]
	v_pk_mul_f32 v[166:167], v[164:165], s[58:59] op_sel_hi:[1,0]
	v_mul_f32_e32 v232, 0x3fb504f3, v207
	v_sub_f32_e32 v235, v245, v206
	v_sub_f32_e32 v234, v244, v206
	v_sub_f32_e32 v237, v247, v206
	v_sub_f32_e32 v236, v246, v206
	v_sub_f32_e32 v213, v213, v206
	v_sub_f32_e32 v212, v212, v206
	v_pk_mul_f32 v[186:187], v[162:163], s[58:59] op_sel_hi:[1,0]
	v_pk_mul_f32 v[190:191], v[174:175], s[58:59] op_sel_hi:[1,0]
	v_pk_fma_f32 v[174:175], v[180:181], 0.5, 0.5 op_sel_hi:[1,0,0]
	v_pk_fma_f32 v[180:181], v[182:183], 0.5, 0.5 op_sel_hi:[1,0,0]
	v_pk_fma_f32 v[182:183], v[238:239], 0.5, 0.5 op_sel_hi:[1,0,0]
	v_pk_fma_f32 v[164:165], v[240:241], 0.5, 0.5 op_sel_hi:[1,0,0]
	v_sub_f32_e32 v239, v249, v206
	v_sub_f32_e32 v238, v248, v206
	v_sub_f32_e32 v241, v251, v206
	v_sub_f32_e32 v240, v250, v206
	v_sub_f32_e32 v217, v217, v206
	v_sub_f32_e32 v216, v216, v206
	v_sub_f32_e32 v219, v219, v206
	v_sub_f32_e32 v218, v218, v206
	v_sub_f32_e32 v207, v215, v206
	v_sub_f32_e32 v206, v214, v206
	v_pk_mul_f32 v[214:215], v[236:237], v[232:233] op_sel_hi:[1,0]
	v_pk_mul_f32 v[234:235], v[234:235], v[232:233] op_sel_hi:[1,0]
	v_pk_mul_f32 v[212:213], v[232:233], v[212:213] op_sel_hi:[0,1]
	v_pk_mul_f32 v[236:237], v[240:241], v[232:233] op_sel_hi:[1,0]
	v_pk_mul_f32 v[238:239], v[238:239], v[232:233] op_sel_hi:[1,0]
	v_pk_mul_f32 v[218:219], v[232:233], v[218:219] op_sel_hi:[0,1]
	v_pk_mul_f32 v[216:217], v[232:233], v[216:217] op_sel_hi:[0,1]
	v_pk_mul_f32 v[206:207], v[232:233], v[206:207] op_sel_hi:[0,1]
	v_pk_fma_f32 v[232:233], v[140:141], v[234:235], v[186:187]
	v_pk_fma_f32 v[214:215], v[142:143], v[214:215], v[166:167]
	v_pk_fma_f32 v[212:213], v[128:129], v[212:213], v[192:193]
	v_pk_fma_f32 v[162:163], v[242:243], 0.5, 0.5 op_sel_hi:[1,0,0]
	v_pk_fma_f32 v[234:235], v[136:137], v[238:239], v[188:189]
	v_pk_fma_f32 v[236:237], v[138:139], v[236:237], v[168:169]
	v_pk_fma_f32 v[216:217], v[132:133], v[216:217], v[190:191]
	v_pk_fma_f32 v[218:219], v[134:135], v[218:219], v[170:171]
	v_pk_fma_f32 v[206:207], v[130:131], v[206:207], v[172:173]
	v_pk_fma_f32 v[126:127], v[126:127], v[174:175], v[214:215]
	v_pk_fma_f32 v[124:125], v[124:125], v[176:177], v[232:233]
	v_pk_fma_f32 v[112:113], v[112:113], v[164:165], v[212:213]
	v_pk_fma_f32 v[122:123], v[122:123], v[178:179], v[236:237]
	v_pk_fma_f32 v[120:121], v[120:121], v[180:181], v[234:235]
	v_pk_fma_f32 v[118:119], v[118:119], v[182:183], v[218:219]
	v_pk_fma_f32 v[116:117], v[116:117], v[184:185], v[216:217]
	v_pk_fma_f32 v[114:115], v[114:115], v[162:163], v[206:207]
	global_store_dwordx4 v[198:199], v[124:127], off
	global_store_dwordx4 v[198:199], v[120:123], off offset:64
	global_store_dwordx4 v[198:199], v[116:119], off offset:512
	global_store_dwordx4 v[198:199], v[112:115], off offset:576
	s_and_b64 vcc, exec, s[6:7]
	s_cbranch_vccnz .Lmy_epi_f0
	s_sleep 60
.Lmy_epi_f0:
	v_add_u32_e32 v212, s25, v227
	v_ashrrev_i32_e32 v213, 31, v212
	v_add_u32_e32 v112, s25, v226
	v_ashrrev_i32_e32 v113, 31, v112
	v_lshlrev_b64 v[206:207], 12, v[112:113]
	v_lshl_add_u64 v[114:115], v[112:113], 3, s[14:15]
	v_lshl_add_u64 v[112:113], s[16:17], 0, v[206:207]
	global_load_dwordx2 v[198:199], v[114:115], off
	v_lshl_add_u64 v[124:125], v[112:113], 0, v[160:161]
	global_load_dwordx4 v[112:115], v[124:125], off
	global_load_dwordx4 v[116:119], v[124:125], off offset:64
	global_load_dwordx4 v[120:123], v[124:125], off offset:512
	s_nop 0
	global_load_dwordx4 v[124:127], v[124:125], off offset:576
	v_lshl_add_u64 v[206:207], s[8:9], 0, v[206:207]
	v_lshl_add_u64 v[206:207], v[206:207], 0, v[160:161]
	v_lshl_add_u64 v[214:215], v[212:213], 3, s[14:15]
	v_lshlrev_b64 v[212:213], 12, v[212:213]
	v_lshl_add_u64 v[216:217], s[16:17], 0, v[212:213]
	v_lshl_add_u64 v[216:217], v[216:217], 0, v[160:161]
	s_waitcnt vmcnt(4)
	v_mul_f32_e32 v218, 0x3fb504f3, v199
	s_waitcnt vmcnt(3)
	v_sub_f32_e32 v113, v113, v198
	v_sub_f32_e32 v112, v112, v198
	v_sub_f32_e32 v115, v115, v198
	v_sub_f32_e32 v114, v114, v198
	s_waitcnt vmcnt(2)
	v_sub_f32_e32 v117, v117, v198
	v_sub_f32_e32 v116, v116, v198
	v_sub_f32_e32 v119, v119, v198
	v_sub_f32_e32 v118, v118, v198
	s_waitcnt vmcnt(1)
	v_sub_f32_e32 v121, v121, v198
	v_sub_f32_e32 v120, v120, v198
	v_sub_f32_e32 v123, v123, v198
	v_sub_f32_e32 v122, v122, v198
	s_waitcnt vmcnt(0)
	v_sub_f32_e32 v125, v125, v198
	v_sub_f32_e32 v124, v124, v198
	v_sub_f32_e32 v127, v127, v198
	v_sub_f32_e32 v126, v126, v198
	v_pk_mul_f32 v[114:115], v[114:115], v[218:219] op_sel_hi:[1,0]
	v_pk_mul_f32 v[112:113], v[112:113], v[218:219] op_sel_hi:[1,0]
	v_pk_mul_f32 v[118:119], v[118:119], v[218:219] op_sel_hi:[1,0]
	v_pk_mul_f32 v[116:117], v[116:117], v[218:219] op_sel_hi:[1,0]
	v_pk_mul_f32 v[122:123], v[218:219], v[122:123] op_sel_hi:[0,1]
	v_pk_mul_f32 v[120:121], v[218:219], v[120:121] op_sel_hi:[0,1]
	v_pk_mul_f32 v[126:127], v[218:219], v[126:127] op_sel_hi:[0,1]
	v_pk_mul_f32 v[124:125], v[218:219], v[124:125] op_sel_hi:[0,1]
	v_pk_fma_f32 v[112:113], v[140:141], v[112:113], v[186:187]
	v_pk_fma_f32 v[114:115], v[142:143], v[114:115], v[166:167]
	v_pk_fma_f32 v[116:117], v[136:137], v[116:117], v[188:189]
	v_pk_fma_f32 v[118:119], v[138:139], v[118:119], v[168:169]
	v_pk_fma_f32 v[120:121], v[132:133], v[120:121], v[190:191]
	v_pk_fma_f32 v[122:123], v[134:135], v[122:123], v[170:171]
	v_pk_fma_f32 v[124:125], v[128:129], v[124:125], v[192:193]
	v_pk_fma_f32 v[126:127], v[130:131], v[126:127], v[172:173]
	v_pk_fma_f32 v[110:111], v[110:111], v[174:175], v[114:115]
	v_pk_fma_f32 v[108:109], v[108:109], v[176:177], v[112:113]
	v_pk_fma_f32 v[106:107], v[106:107], v[178:179], v[118:119]
	v_pk_fma_f32 v[104:105], v[104:105], v[180:181], v[116:117]
	v_pk_fma_f32 v[102:103], v[102:103], v[182:183], v[122:123]
	v_pk_fma_f32 v[100:101], v[100:101], v[184:185], v[120:121]
	v_pk_fma_f32 v[98:99], v[98:99], v[162:163], v[126:127]
	v_pk_fma_f32 v[96:97], v[96:97], v[164:165], v[124:125]
	global_store_dwordx4 v[206:207], v[108:111], off
	global_store_dwordx4 v[206:207], v[104:107], off offset:64
	global_store_dwordx4 v[206:207], v[100:103], off offset:512
	global_store_dwordx4 v[206:207], v[96:99], off offset:576
	s_and_b64 vcc, exec, s[6:7]
	s_cbranch_vccnz .Lmy_epi_f1
	s_sleep 60
.Lmy_epi_f1:
	global_load_dwordx2 v[112:113], v[214:215], off
	global_load_dwordx4 v[96:99], v[216:217], off
	global_load_dwordx4 v[100:103], v[216:217], off offset:64
	global_load_dwordx4 v[104:107], v[216:217], off offset:512
	global_load_dwordx4 v[108:111], v[216:217], off offset:576
	v_add_u32_e32 v114, s25, v228
	v_lshl_add_u64 v[118:119], s[8:9], 0, v[212:213]
	v_ashrrev_i32_e32 v115, 31, v114
	v_lshl_add_u64 v[118:119], v[118:119], 0, v[160:161]
	v_lshl_add_u64 v[116:117], v[114:115], 3, s[14:15]
	v_lshlrev_b64 v[114:115], 12, v[114:115]
	v_lshl_add_u64 v[120:121], s[16:17], 0, v[114:115]
	v_lshl_add_u64 v[120:121], v[120:121], 0, v[160:161]
	s_waitcnt vmcnt(4)
	v_mul_f32_e32 v122, 0x3fb504f3, v113
	s_waitcnt vmcnt(3)
	v_sub_f32_e32 v97, v97, v112
	v_sub_f32_e32 v96, v96, v112
	v_sub_f32_e32 v99, v99, v112
	v_sub_f32_e32 v98, v98, v112
	s_waitcnt vmcnt(2)
	v_sub_f32_e32 v101, v101, v112
	v_sub_f32_e32 v100, v100, v112
	v_sub_f32_e32 v103, v103, v112
	v_sub_f32_e32 v102, v102, v112
	s_waitcnt vmcnt(1)
	v_sub_f32_e32 v105, v105, v112
	v_sub_f32_e32 v104, v104, v112
	v_sub_f32_e32 v107, v107, v112
	v_sub_f32_e32 v106, v106, v112
	s_waitcnt vmcnt(0)
	v_sub_f32_e32 v109, v109, v112
	v_sub_f32_e32 v108, v108, v112
	v_sub_f32_e32 v111, v111, v112
	v_sub_f32_e32 v110, v110, v112
	v_pk_mul_f32 v[98:99], v[98:99], v[122:123] op_sel_hi:[1,0]
	v_pk_mul_f32 v[96:97], v[96:97], v[122:123] op_sel_hi:[1,0]
	v_pk_mul_f32 v[102:103], v[102:103], v[122:123] op_sel_hi:[1,0]
	v_pk_mul_f32 v[100:101], v[100:101], v[122:123] op_sel_hi:[1,0]
	v_pk_mul_f32 v[106:107], v[122:123], v[106:107] op_sel_hi:[0,1]
	v_pk_mul_f32 v[104:105], v[122:123], v[104:105] op_sel_hi:[0,1]
	v_pk_mul_f32 v[110:111], v[122:123], v[110:111] op_sel_hi:[0,1]
	v_pk_mul_f32 v[108:109], v[122:123], v[108:109] op_sel_hi:[0,1]
	v_pk_fma_f32 v[96:97], v[140:141], v[96:97], v[186:187]
	v_pk_fma_f32 v[98:99], v[142:143], v[98:99], v[166:167]
	v_pk_fma_f32 v[100:101], v[136:137], v[100:101], v[188:189]
	v_pk_fma_f32 v[102:103], v[138:139], v[102:103], v[168:169]
	v_pk_fma_f32 v[104:105], v[132:133], v[104:105], v[190:191]
	v_pk_fma_f32 v[106:107], v[134:135], v[106:107], v[170:171]
	v_pk_fma_f32 v[108:109], v[128:129], v[108:109], v[192:193]
	v_pk_fma_f32 v[110:111], v[130:131], v[110:111], v[172:173]
	v_pk_fma_f32 v[94:95], v[94:95], v[174:175], v[98:99]
	v_pk_fma_f32 v[92:93], v[92:93], v[176:177], v[96:97]
	v_pk_fma_f32 v[90:91], v[90:91], v[178:179], v[102:103]
	v_pk_fma_f32 v[88:89], v[88:89], v[180:181], v[100:101]
	v_pk_fma_f32 v[86:87], v[86:87], v[182:183], v[106:107]
	v_pk_fma_f32 v[84:85], v[84:85], v[184:185], v[104:105]
	v_pk_fma_f32 v[82:83], v[82:83], v[162:163], v[110:111]
	v_pk_fma_f32 v[80:81], v[80:81], v[164:165], v[108:109]
	global_store_dwordx4 v[118:119], v[92:95], off
	global_store_dwordx4 v[118:119], v[88:91], off offset:64
	global_store_dwordx4 v[118:119], v[84:87], off offset:512
	global_store_dwordx4 v[118:119], v[80:83], off offset:576
	s_and_b64 vcc, exec, s[6:7]
	s_cbranch_vccnz .Lmy_epi_f2
	s_sleep 60
.Lmy_epi_f2:
	global_load_dwordx2 v[96:97], v[116:117], off
	global_load_dwordx4 v[80:83], v[120:121], off
	global_load_dwordx4 v[84:87], v[120:121], off offset:64
	global_load_dwordx4 v[88:91], v[120:121], off offset:512
	global_load_dwordx4 v[92:95], v[120:121], off offset:576
	v_add_u32_e32 v98, 0x80, v194
	v_lshl_add_u64 v[100:101], s[8:9], 0, v[114:115]
	v_ashrrev_i32_e32 v99, 31, v98
	v_lshl_add_u64 v[100:101], v[100:101], 0, v[160:161]
	v_lshl_add_u64 v[102:103], v[98:99], 3, s[14:15]
	v_lshlrev_b64 v[98:99], 12, v[98:99]
	v_lshl_add_u64 v[104:105], s[16:17], 0, v[98:99]
	v_lshl_add_u64 v[104:105], v[104:105], 0, v[160:161]
	s_waitcnt vmcnt(4)
	v_mul_f32_e32 v106, 0x3fb504f3, v97
	s_waitcnt vmcnt(3)
	v_sub_f32_e32 v81, v81, v96
	v_sub_f32_e32 v80, v80, v96
	v_sub_f32_e32 v83, v83, v96
	v_sub_f32_e32 v82, v82, v96
	s_waitcnt vmcnt(2)
	v_sub_f32_e32 v85, v85, v96
	v_sub_f32_e32 v84, v84, v96
	v_sub_f32_e32 v87, v87, v96
	v_sub_f32_e32 v86, v86, v96
	s_waitcnt vmcnt(1)
	v_sub_f32_e32 v89, v89, v96
	v_sub_f32_e32 v88, v88, v96
	v_sub_f32_e32 v91, v91, v96
	v_sub_f32_e32 v90, v90, v96
	s_waitcnt vmcnt(0)
	v_sub_f32_e32 v93, v93, v96
	v_sub_f32_e32 v92, v92, v96
	v_sub_f32_e32 v95, v95, v96
	v_sub_f32_e32 v94, v94, v96
	v_pk_mul_f32 v[82:83], v[82:83], v[106:107] op_sel_hi:[1,0]
	v_pk_mul_f32 v[80:81], v[80:81], v[106:107] op_sel_hi:[1,0]
	v_pk_mul_f32 v[86:87], v[86:87], v[106:107] op_sel_hi:[1,0]
	v_pk_mul_f32 v[84:85], v[84:85], v[106:107] op_sel_hi:[1,0]
	v_pk_mul_f32 v[90:91], v[106:107], v[90:91] op_sel_hi:[0,1]
	v_pk_mul_f32 v[88:89], v[106:107], v[88:89] op_sel_hi:[0,1]
	v_pk_mul_f32 v[94:95], v[106:107], v[94:95] op_sel_hi:[0,1]
	v_pk_mul_f32 v[92:93], v[106:107], v[92:93] op_sel_hi:[0,1]
	v_pk_fma_f32 v[80:81], v[140:141], v[80:81], v[186:187]
	v_pk_fma_f32 v[82:83], v[142:143], v[82:83], v[166:167]
	v_pk_fma_f32 v[84:85], v[136:137], v[84:85], v[188:189]
	v_pk_fma_f32 v[86:87], v[138:139], v[86:87], v[168:169]
	v_pk_fma_f32 v[88:89], v[132:133], v[88:89], v[190:191]
	v_pk_fma_f32 v[90:91], v[134:135], v[90:91], v[170:171]
	v_pk_fma_f32 v[92:93], v[128:129], v[92:93], v[192:193]
	v_pk_fma_f32 v[94:95], v[130:131], v[94:95], v[172:173]
	v_pk_fma_f32 v[78:79], v[78:79], v[174:175], v[82:83]
	v_pk_fma_f32 v[76:77], v[76:77], v[176:177], v[80:81]
	v_pk_fma_f32 v[74:75], v[74:75], v[178:179], v[86:87]
	v_pk_fma_f32 v[72:73], v[72:73], v[180:181], v[84:85]
	v_pk_fma_f32 v[70:71], v[70:71], v[182:183], v[90:91]
	v_pk_fma_f32 v[68:69], v[68:69], v[184:185], v[88:89]
	v_pk_fma_f32 v[66:67], v[66:67], v[162:163], v[94:95]
	v_pk_fma_f32 v[64:65], v[64:65], v[164:165], v[92:93]
	global_store_dwordx4 v[100:101], v[76:79], off
	global_store_dwordx4 v[100:101], v[72:75], off offset:64
	global_store_dwordx4 v[100:101], v[68:71], off offset:512
	global_store_dwordx4 v[100:101], v[64:67], off offset:576
	global_load_dwordx2 v[80:81], v[102:103], off
	global_load_dwordx4 v[64:67], v[104:105], off
	global_load_dwordx4 v[68:71], v[104:105], off offset:64
	global_load_dwordx4 v[72:75], v[104:105], off offset:512
	global_load_dwordx4 v[76:79], v[104:105], off offset:576
	v_add_u32_e32 v82, 0x90, v194
	v_lshl_add_u64 v[86:87], s[8:9], 0, v[98:99]
	v_ashrrev_i32_e32 v83, 31, v82
	v_lshl_add_u64 v[86:87], v[86:87], 0, v[160:161]
	v_lshl_add_u64 v[84:85], v[82:83], 3, s[14:15]
	v_lshlrev_b64 v[82:83], 12, v[82:83]
	v_lshl_add_u64 v[88:89], s[16:17], 0, v[82:83]
	v_lshl_add_u64 v[88:89], v[88:89], 0, v[160:161]
	s_waitcnt vmcnt(4)
	v_mul_f32_e32 v90, 0x3fb504f3, v81
	s_waitcnt vmcnt(3)
	v_sub_f32_e32 v65, v65, v80
	v_sub_f32_e32 v64, v64, v80
	v_sub_f32_e32 v67, v67, v80
	v_sub_f32_e32 v66, v66, v80
	s_waitcnt vmcnt(2)
	v_sub_f32_e32 v69, v69, v80
	v_sub_f32_e32 v68, v68, v80
	v_sub_f32_e32 v71, v71, v80
	v_sub_f32_e32 v70, v70, v80
	s_waitcnt vmcnt(1)
	v_sub_f32_e32 v73, v73, v80
	v_sub_f32_e32 v72, v72, v80
	v_sub_f32_e32 v75, v75, v80
	v_sub_f32_e32 v74, v74, v80
	s_waitcnt vmcnt(0)
	v_sub_f32_e32 v77, v77, v80
	v_sub_f32_e32 v76, v76, v80
	v_sub_f32_e32 v79, v79, v80
	v_sub_f32_e32 v78, v78, v80
	v_pk_mul_f32 v[66:67], v[66:67], v[90:91] op_sel_hi:[1,0]
	v_pk_mul_f32 v[64:65], v[64:65], v[90:91] op_sel_hi:[1,0]
	v_pk_mul_f32 v[70:71], v[70:71], v[90:91] op_sel_hi:[1,0]
	v_pk_mul_f32 v[68:69], v[68:69], v[90:91] op_sel_hi:[1,0]
	v_pk_mul_f32 v[74:75], v[90:91], v[74:75] op_sel_hi:[0,1]
	v_pk_mul_f32 v[72:73], v[90:91], v[72:73] op_sel_hi:[0,1]
	v_pk_mul_f32 v[78:79], v[90:91], v[78:79] op_sel_hi:[0,1]
	v_pk_mul_f32 v[76:77], v[90:91], v[76:77] op_sel_hi:[0,1]
	v_pk_fma_f32 v[64:65], v[140:141], v[64:65], v[186:187]
	v_pk_fma_f32 v[66:67], v[142:143], v[66:67], v[166:167]
	v_pk_fma_f32 v[68:69], v[136:137], v[68:69], v[188:189]
	v_pk_fma_f32 v[70:71], v[138:139], v[70:71], v[168:169]
	v_pk_fma_f32 v[72:73], v[132:133], v[72:73], v[190:191]
	v_pk_fma_f32 v[74:75], v[134:135], v[74:75], v[170:171]
	v_pk_fma_f32 v[76:77], v[128:129], v[76:77], v[192:193]
	v_pk_fma_f32 v[78:79], v[130:131], v[78:79], v[172:173]
	v_pk_fma_f32 v[62:63], v[62:63], v[174:175], v[66:67]
	v_pk_fma_f32 v[60:61], v[60:61], v[176:177], v[64:65]
	v_pk_fma_f32 v[58:59], v[58:59], v[178:179], v[70:71]
	v_pk_fma_f32 v[56:57], v[56:57], v[180:181], v[68:69]
	v_pk_fma_f32 v[54:55], v[54:55], v[182:183], v[74:75]
	v_pk_fma_f32 v[52:53], v[52:53], v[184:185], v[72:73]
	v_pk_fma_f32 v[50:51], v[50:51], v[162:163], v[78:79]
	v_pk_fma_f32 v[48:49], v[48:49], v[164:165], v[76:77]
	global_store_dwordx4 v[86:87], v[60:63], off
	global_store_dwordx4 v[86:87], v[56:59], off offset:64
	global_store_dwordx4 v[86:87], v[52:55], off offset:512
	global_store_dwordx4 v[86:87], v[48:51], off offset:576
	global_load_dwordx2 v[64:65], v[84:85], off
	global_load_dwordx4 v[48:51], v[88:89], off
	global_load_dwordx4 v[52:55], v[88:89], off offset:64
	global_load_dwordx4 v[56:59], v[88:89], off offset:512
	global_load_dwordx4 v[60:63], v[88:89], off offset:576
	v_add_u32_e32 v66, 0xa0, v194
	v_lshl_add_u64 v[70:71], s[8:9], 0, v[82:83]
	v_ashrrev_i32_e32 v67, 31, v66
	v_lshl_add_u64 v[70:71], v[70:71], 0, v[160:161]
	v_lshl_add_u64 v[68:69], v[66:67], 3, s[14:15]
	v_lshlrev_b64 v[66:67], 12, v[66:67]
	v_lshl_add_u64 v[72:73], s[16:17], 0, v[66:67]
	v_lshl_add_u64 v[72:73], v[72:73], 0, v[160:161]
	s_waitcnt vmcnt(4)
	v_mul_f32_e32 v74, 0x3fb504f3, v65
	s_waitcnt vmcnt(3)
	v_sub_f32_e32 v49, v49, v64
	v_sub_f32_e32 v48, v48, v64
	v_sub_f32_e32 v51, v51, v64
	v_sub_f32_e32 v50, v50, v64
	s_waitcnt vmcnt(2)
	v_sub_f32_e32 v53, v53, v64
	v_sub_f32_e32 v52, v52, v64
	v_sub_f32_e32 v55, v55, v64
	v_sub_f32_e32 v54, v54, v64
	s_waitcnt vmcnt(1)
	v_sub_f32_e32 v57, v57, v64
	v_sub_f32_e32 v56, v56, v64
	v_sub_f32_e32 v59, v59, v64
	v_sub_f32_e32 v58, v58, v64
	s_waitcnt vmcnt(0)
	v_sub_f32_e32 v61, v61, v64
	v_sub_f32_e32 v60, v60, v64
	v_sub_f32_e32 v63, v63, v64
	v_sub_f32_e32 v62, v62, v64
	v_pk_mul_f32 v[50:51], v[50:51], v[74:75] op_sel_hi:[1,0]
	v_pk_mul_f32 v[48:49], v[48:49], v[74:75] op_sel_hi:[1,0]
	v_pk_mul_f32 v[54:55], v[54:55], v[74:75] op_sel_hi:[1,0]
	v_pk_mul_f32 v[52:53], v[52:53], v[74:75] op_sel_hi:[1,0]
	v_pk_mul_f32 v[58:59], v[74:75], v[58:59] op_sel_hi:[0,1]
	v_pk_mul_f32 v[56:57], v[74:75], v[56:57] op_sel_hi:[0,1]
	v_pk_mul_f32 v[62:63], v[74:75], v[62:63] op_sel_hi:[0,1]
	v_pk_mul_f32 v[60:61], v[74:75], v[60:61] op_sel_hi:[0,1]
	v_pk_fma_f32 v[48:49], v[140:141], v[48:49], v[186:187]
	v_pk_fma_f32 v[50:51], v[142:143], v[50:51], v[166:167]
	v_pk_fma_f32 v[52:53], v[136:137], v[52:53], v[188:189]
	v_pk_fma_f32 v[54:55], v[138:139], v[54:55], v[168:169]
	v_pk_fma_f32 v[56:57], v[132:133], v[56:57], v[190:191]
	v_pk_fma_f32 v[58:59], v[134:135], v[58:59], v[170:171]
	v_pk_fma_f32 v[60:61], v[128:129], v[60:61], v[192:193]
	v_pk_fma_f32 v[62:63], v[130:131], v[62:63], v[172:173]
	v_pk_fma_f32 v[46:47], v[46:47], v[174:175], v[50:51]
	v_pk_fma_f32 v[44:45], v[44:45], v[176:177], v[48:49]
	v_pk_fma_f32 v[42:43], v[42:43], v[178:179], v[54:55]
	v_pk_fma_f32 v[40:41], v[40:41], v[180:181], v[52:53]
	v_pk_fma_f32 v[38:39], v[38:39], v[182:183], v[58:59]
	v_pk_fma_f32 v[36:37], v[36:37], v[184:185], v[56:57]
	v_pk_fma_f32 v[34:35], v[34:35], v[162:163], v[62:63]
	v_pk_fma_f32 v[32:33], v[32:33], v[164:165], v[60:61]
	global_store_dwordx4 v[70:71], v[44:47], off
	global_store_dwordx4 v[70:71], v[40:43], off offset:64
	global_store_dwordx4 v[70:71], v[36:39], off offset:512
	global_store_dwordx4 v[70:71], v[32:35], off offset:576
	global_load_dwordx2 v[48:49], v[68:69], off
	global_load_dwordx4 v[32:35], v[72:73], off
	global_load_dwordx4 v[36:39], v[72:73], off offset:64
	global_load_dwordx4 v[40:43], v[72:73], off offset:512
	global_load_dwordx4 v[44:47], v[72:73], off offset:576
	v_add_u32_e32 v50, 0xb0, v194
	v_lshl_add_u64 v[54:55], s[8:9], 0, v[66:67]
	v_ashrrev_i32_e32 v51, 31, v50
	v_lshl_add_u64 v[54:55], v[54:55], 0, v[160:161]
	v_lshl_add_u64 v[52:53], v[50:51], 3, s[14:15]
	v_lshlrev_b64 v[50:51], 12, v[50:51]
	v_lshl_add_u64 v[56:57], s[16:17], 0, v[50:51]
	v_lshl_add_u64 v[56:57], v[56:57], 0, v[160:161]
	s_waitcnt vmcnt(4)
	v_mul_f32_e32 v58, 0x3fb504f3, v49
	s_waitcnt vmcnt(3)
	v_sub_f32_e32 v33, v33, v48
	v_sub_f32_e32 v32, v32, v48
	v_sub_f32_e32 v35, v35, v48
	v_sub_f32_e32 v34, v34, v48
	s_waitcnt vmcnt(2)
	v_sub_f32_e32 v37, v37, v48
	v_sub_f32_e32 v36, v36, v48
	v_sub_f32_e32 v39, v39, v48
	v_sub_f32_e32 v38, v38, v48
	s_waitcnt vmcnt(1)
	v_sub_f32_e32 v41, v41, v48
	v_sub_f32_e32 v40, v40, v48
	v_sub_f32_e32 v43, v43, v48
	v_sub_f32_e32 v42, v42, v48
	s_waitcnt vmcnt(0)
	v_sub_f32_e32 v45, v45, v48
	v_sub_f32_e32 v44, v44, v48
	v_sub_f32_e32 v47, v47, v48
	v_sub_f32_e32 v46, v46, v48
	v_pk_mul_f32 v[34:35], v[34:35], v[58:59] op_sel_hi:[1,0]
	v_pk_mul_f32 v[32:33], v[32:33], v[58:59] op_sel_hi:[1,0]
	v_pk_mul_f32 v[38:39], v[38:39], v[58:59] op_sel_hi:[1,0]
	v_pk_mul_f32 v[36:37], v[36:37], v[58:59] op_sel_hi:[1,0]
	v_pk_mul_f32 v[42:43], v[58:59], v[42:43] op_sel_hi:[0,1]
	v_pk_mul_f32 v[40:41], v[58:59], v[40:41] op_sel_hi:[0,1]
	v_pk_mul_f32 v[46:47], v[58:59], v[46:47] op_sel_hi:[0,1]
	v_pk_mul_f32 v[44:45], v[58:59], v[44:45] op_sel_hi:[0,1]
	v_pk_fma_f32 v[32:33], v[140:141], v[32:33], v[186:187]
	v_pk_fma_f32 v[34:35], v[142:143], v[34:35], v[166:167]
	v_pk_fma_f32 v[36:37], v[136:137], v[36:37], v[188:189]
	v_pk_fma_f32 v[38:39], v[138:139], v[38:39], v[168:169]
	v_pk_fma_f32 v[40:41], v[132:133], v[40:41], v[190:191]
	v_pk_fma_f32 v[42:43], v[134:135], v[42:43], v[170:171]
	v_pk_fma_f32 v[44:45], v[128:129], v[44:45], v[192:193]
	v_pk_fma_f32 v[46:47], v[130:131], v[46:47], v[172:173]
	v_pk_fma_f32 v[30:31], v[30:31], v[174:175], v[34:35]
	v_pk_fma_f32 v[28:29], v[28:29], v[176:177], v[32:33]
	v_pk_fma_f32 v[26:27], v[26:27], v[178:179], v[38:39]
	v_pk_fma_f32 v[24:25], v[24:25], v[180:181], v[36:37]
	v_pk_fma_f32 v[22:23], v[22:23], v[182:183], v[42:43]
	v_pk_fma_f32 v[20:21], v[20:21], v[184:185], v[40:41]
	v_pk_fma_f32 v[18:19], v[18:19], v[162:163], v[46:47]
	v_pk_fma_f32 v[16:17], v[16:17], v[164:165], v[44:45]
	global_store_dwordx4 v[54:55], v[28:31], off
	global_store_dwordx4 v[54:55], v[24:27], off offset:64
	global_store_dwordx4 v[54:55], v[20:23], off offset:512
	global_store_dwordx4 v[54:55], v[16:19], off offset:576
	global_load_dwordx2 v[32:33], v[52:53], off
	global_load_dwordx4 v[16:19], v[56:57], off
	global_load_dwordx4 v[20:23], v[56:57], off offset:64
	global_load_dwordx4 v[24:27], v[56:57], off offset:512
	global_load_dwordx4 v[28:31], v[56:57], off offset:576
	v_lshl_add_u64 v[34:35], s[8:9], 0, v[50:51]
	v_lshl_add_u64 v[34:35], v[34:35], 0, v[160:161]
	s_waitcnt vmcnt(4)
	v_mul_f32_e32 v36, 0x3fb504f3, v33
	s_waitcnt vmcnt(3)
	v_sub_f32_e32 v17, v17, v32
	v_sub_f32_e32 v16, v16, v32
	v_sub_f32_e32 v19, v19, v32
	v_sub_f32_e32 v18, v18, v32
	s_waitcnt vmcnt(2)
	v_sub_f32_e32 v21, v21, v32
	v_sub_f32_e32 v20, v20, v32
	v_sub_f32_e32 v23, v23, v32
	v_sub_f32_e32 v22, v22, v32
	s_waitcnt vmcnt(1)
	v_sub_f32_e32 v25, v25, v32
	v_sub_f32_e32 v24, v24, v32
	v_sub_f32_e32 v27, v27, v32
	v_sub_f32_e32 v26, v26, v32
	s_waitcnt vmcnt(0)
	v_sub_f32_e32 v29, v29, v32
	v_sub_f32_e32 v28, v28, v32
	v_sub_f32_e32 v31, v31, v32
	v_sub_f32_e32 v30, v30, v32
	v_pk_mul_f32 v[18:19], v[18:19], v[36:37] op_sel_hi:[1,0]
	v_pk_mul_f32 v[16:17], v[16:17], v[36:37] op_sel_hi:[1,0]
	v_pk_mul_f32 v[22:23], v[22:23], v[36:37] op_sel_hi:[1,0]
	v_pk_mul_f32 v[20:21], v[20:21], v[36:37] op_sel_hi:[1,0]
	v_pk_mul_f32 v[26:27], v[36:37], v[26:27] op_sel_hi:[0,1]
	v_pk_mul_f32 v[24:25], v[36:37], v[24:25] op_sel_hi:[0,1]
	v_pk_mul_f32 v[30:31], v[36:37], v[30:31] op_sel_hi:[0,1]
	v_pk_mul_f32 v[28:29], v[36:37], v[28:29] op_sel_hi:[0,1]
	v_pk_fma_f32 v[16:17], v[140:141], v[16:17], v[186:187]
	v_pk_fma_f32 v[18:19], v[142:143], v[18:19], v[166:167]
	v_pk_fma_f32 v[20:21], v[136:137], v[20:21], v[188:189]
	v_pk_fma_f32 v[22:23], v[138:139], v[22:23], v[168:169]
	v_pk_fma_f32 v[24:25], v[132:133], v[24:25], v[190:191]
	v_pk_fma_f32 v[26:27], v[134:135], v[26:27], v[170:171]
	v_pk_fma_f32 v[28:29], v[128:129], v[28:29], v[192:193]
	v_pk_fma_f32 v[30:31], v[130:131], v[30:31], v[172:173]
	v_pk_fma_f32 v[14:15], v[14:15], v[174:175], v[18:19]
	v_pk_fma_f32 v[12:13], v[12:13], v[176:177], v[16:17]
	v_pk_fma_f32 v[10:11], v[10:11], v[178:179], v[22:23]
	v_pk_fma_f32 v[8:9], v[8:9], v[180:181], v[20:21]
	v_pk_fma_f32 v[6:7], v[6:7], v[182:183], v[26:27]
	v_pk_fma_f32 v[4:5], v[4:5], v[184:185], v[24:25]
	v_pk_fma_f32 v[2:3], v[2:3], v[162:163], v[30:31]
	v_pk_fma_f32 v[0:1], v[0:1], v[164:165], v[28:29]
	global_store_dwordx4 v[34:35], v[12:15], off
	global_store_dwordx4 v[34:35], v[8:11], off offset:64
	global_store_dwordx4 v[34:35], v[4:7], off offset:512
	global_store_dwordx4 v[34:35], v[0:3], off offset:576
	s_and_b64 vcc, exec, s[6:7]
	s_mov_b64 s[6:7], -1
	s_cbranch_vccnz .LBB0_1365
